# adds B tile-loop cleanup: second score tile uses -m splat directly as srcC (no 8 v_mov_b64/tile), no pad nops after inline max3, MFMA->VALU pad trimmed
# speedup vs baseline: 1.0086x; 1.0008x over previous
.LBB0_495:
	s_mul_i32 s52, s51, 0x5800
	v_add_u32_e32 v54, s52, v131
	ds_read_b128 v[50:53], v54 offset:0
	ds_read_b128 v[166:169], v54 offset:32
	ds_read_b128 v[170:173], v54 offset:64
	ds_read_b128 v[194:197], v54 offset:0x60
	ds_read_b128 v[200:203], v54 offset:0x80
	ds_read_b128 v[212:215], v54 offset:0xa0
	ds_read_b128 v[216:219], v54 offset:0x1a00
	ds_read_b128 v[220:223], v54 offset:0x1a20
	ds_read_b128 v[224:227], v54 offset:0x1a40
	ds_read_b128 v[228:231], v54 offset:0x1a60
	ds_read_b128 v[232:235], v54 offset:0x1a80
	ds_read_b128 v[236:239], v54 offset:0x1aa0
	s_waitcnt lgkmcnt(0)
	s_nop 0
	s_nop 0
	v_mfma_f32_32x32x16_bf16 v[66:81], v[50:53], v[82:85], v[34:49]
	v_mfma_f32_32x32x16_bf16 v[66:81], v[166:169], v[86:89], v[66:81]
	s_cmp_le_i32 s49, s1
	v_mfma_f32_32x32x16_bf16 v[50:65], v[216:219], v[82:85], v[34:49]
	v_mfma_f32_32x32x16_bf16 v[50:65], v[220:223], v[86:89], v[50:65]
	v_mfma_f32_32x32x16_bf16 v[66:81], v[170:173], v[90:93], v[66:81]
	v_mfma_f32_32x32x16_bf16 v[50:65], v[224:227], v[90:93], v[50:65]
	v_mfma_f32_32x32x16_bf16 v[66:81], v[194:197], v[94:97], v[66:81]
	v_mfma_f32_32x32x16_bf16 v[50:65], v[228:231], v[94:97], v[50:65]
	v_mfma_f32_32x32x16_bf16 v[66:81], v[200:203], v[98:101], v[66:81]
	v_mfma_f32_32x32x16_bf16 v[50:65], v[232:235], v[98:101], v[50:65]
	v_mfma_f32_32x32x16_bf16 v[66:81], v[212:215], v[102:105], v[66:81]
	v_mfma_f32_32x32x16_bf16 v[50:65], v[236:239], v[102:105], v[50:65]
	s_cbranch_scc1 .LBB0_497
	v_add_u32_e32 v137, s49, v145
	v_subrev_u32_e32 v138, 63, v137
	v_cmp_gt_i32_e32 vcc, v138, v163
	v_subrev_u32_e32 v141, 31, v137
	s_nop 5
	v_cndmask_b32_e32 v66, v66, v208, vcc
	v_cmp_gt_i32_e32 vcc, v141, v163
	s_nop 1
	v_cndmask_b32_e32 v50, v50, v208, vcc
	v_cmp_lt_i32_e32 vcc, v138, v163
	v_subrev_u32_e32 v138, 30, v137
	s_nop 0
	v_cndmask_b32_e32 v67, v208, v67, vcc
	v_cmp_le_i32_e32 vcc, v138, v163
	v_subrev_u32_e32 v138, 61, v137
	s_nop 0
	v_cndmask_b32_e32 v51, v208, v51, vcc
	v_cmp_le_i32_e32 vcc, v138, v163
	v_subrev_u32_e32 v138, 29, v137
	s_nop 0
	v_cndmask_b32_e32 v68, v208, v68, vcc
	v_cmp_le_i32_e32 vcc, v138, v163
	v_subrev_u32_e32 v138, 60, v137
	s_nop 0
	v_cndmask_b32_e32 v52, v208, v52, vcc
	v_cmp_le_i32_e32 vcc, v138, v163
	v_subrev_u32_e32 v138, 28, v137
	s_nop 0
	v_cndmask_b32_e32 v69, v208, v69, vcc
	v_cmp_le_i32_e32 vcc, v138, v163
	v_subrev_u32_e32 v138, 55, v137
	s_nop 0
	v_cndmask_b32_e32 v53, v208, v53, vcc
	v_cmp_le_i32_e32 vcc, v138, v163
	v_subrev_u32_e32 v138, 23, v137
	s_nop 0
	v_cndmask_b32_e32 v70, v208, v70, vcc
	v_cmp_le_i32_e32 vcc, v138, v163
	v_subrev_u32_e32 v138, 54, v137
	s_nop 0
	v_cndmask_b32_e32 v54, v208, v54, vcc
	v_cmp_le_i32_e32 vcc, v138, v163
	v_subrev_u32_e32 v138, 22, v137
	s_nop 0
	v_cndmask_b32_e32 v71, v208, v71, vcc
	v_cmp_le_i32_e32 vcc, v138, v163
	v_subrev_u32_e32 v138, 53, v137
	s_nop 0
	v_cndmask_b32_e32 v55, v208, v55, vcc
	v_cmp_le_i32_e32 vcc, v138, v163
	v_subrev_u32_e32 v138, 21, v137
	s_nop 0
	v_cndmask_b32_e32 v72, v208, v72, vcc
	v_cmp_le_i32_e32 vcc, v138, v163
	v_subrev_u32_e32 v138, 52, v137
	s_nop 0
	v_cndmask_b32_e32 v56, v208, v56, vcc
	v_cmp_le_i32_e32 vcc, v138, v163
	v_subrev_u32_e32 v138, 20, v137
	s_nop 0
	v_cndmask_b32_e32 v73, v208, v73, vcc
	v_cmp_le_i32_e32 vcc, v138, v163
	v_subrev_u32_e32 v138, 47, v137
	s_nop 0
	v_cndmask_b32_e32 v57, v208, v57, vcc
	v_cmp_le_i32_e32 vcc, v138, v163
	v_add_u32_e32 v138, -15, v137
	s_nop 0
	v_cndmask_b32_e32 v74, v208, v74, vcc
	v_cmp_le_i32_e32 vcc, v138, v163
	v_subrev_u32_e32 v138, 46, v137
	s_nop 0
	v_cndmask_b32_e32 v58, v208, v58, vcc
	v_cmp_le_i32_e32 vcc, v138, v163
	v_add_u32_e32 v138, -14, v137
	s_nop 0
	v_cndmask_b32_e32 v75, v208, v75, vcc
	v_cmp_le_i32_e32 vcc, v138, v163
	v_subrev_u32_e32 v138, 45, v137
	s_nop 0
	v_cndmask_b32_e32 v59, v208, v59, vcc
	v_cmp_le_i32_e32 vcc, v138, v163
	v_add_u32_e32 v138, -13, v137
	s_nop 0
	v_cndmask_b32_e32 v76, v208, v76, vcc
	v_cmp_le_i32_e32 vcc, v138, v163
	v_subrev_u32_e32 v138, 44, v137
	s_nop 0
	v_cndmask_b32_e32 v60, v208, v60, vcc
	v_cmp_le_i32_e32 vcc, v138, v163
	v_add_u32_e32 v138, -12, v137
	s_nop 0
	v_cndmask_b32_e32 v77, v208, v77, vcc
	v_cmp_le_i32_e32 vcc, v138, v163
	v_subrev_u32_e32 v138, 39, v137
	s_nop 0
	v_cndmask_b32_e32 v61, v208, v61, vcc
	v_cmp_le_i32_e32 vcc, v138, v163
	v_add_u32_e32 v138, -7, v137
	s_nop 0
	v_cndmask_b32_e32 v78, v208, v78, vcc
	v_cmp_le_i32_e32 vcc, v138, v163
	v_subrev_u32_e32 v138, 38, v137
	s_nop 0
	v_cndmask_b32_e32 v62, v208, v62, vcc
	v_cmp_le_i32_e32 vcc, v138, v163
	v_add_u32_e32 v138, -6, v137
	s_nop 0
	v_cndmask_b32_e32 v79, v208, v79, vcc
	v_cmp_le_i32_e32 vcc, v138, v163
	v_subrev_u32_e32 v138, 37, v137
	s_nop 0
	v_cndmask_b32_e32 v63, v208, v63, vcc
	v_cmp_le_i32_e32 vcc, v138, v163
	v_add_u32_e32 v138, -5, v137
	s_nop 0
	v_cndmask_b32_e32 v80, v208, v80, vcc
	v_cmp_le_i32_e32 vcc, v138, v163
	v_subrev_u32_e32 v138, 36, v137
	v_add_u32_e32 v137, -4, v137
	v_cndmask_b32_e32 v64, v208, v64, vcc
	v_cmp_le_i32_e32 vcc, v138, v163
	s_nop 1
	v_cndmask_b32_e32 v81, v208, v81, vcc
	v_cmp_le_i32_e32 vcc, v137, v163
	s_nop 1
	v_cndmask_b32_e32 v65, v208, v65, vcc
.LBB0_497:
	s_nop 12
	s_xor_b64 s[24:25], s[24:25], -1
	v_max3_f32 v137, v208, v66, v50
	s_and_b64 vcc, exec, s[24:25]
	v_max3_f32 v137, v137, v67, v51
	v_max3_f32 v137, v137, v68, v52
	v_max3_f32 v137, v137, v69, v53
	v_max3_f32 v137, v137, v70, v54
	v_max3_f32 v137, v137, v71, v55
	v_max3_f32 v137, v137, v72, v56
	v_max3_f32 v137, v137, v73, v57
	v_max3_f32 v137, v137, v74, v58
	v_max3_f32 v137, v137, v75, v59
	v_max3_f32 v137, v137, v76, v60
	v_max3_f32 v137, v137, v77, v61
	v_max3_f32 v137, v137, v78, v62
	v_max3_f32 v137, v137, v79, v63
	v_max3_f32 v137, v137, v80, v64
	v_max3_f32 v137, v137, v81, v65
	v_mov_b32_e32 v138, v137
	s_nop 1
	v_permlane32_swap_b32_e32 v137, v138
	v_max_f32_e32 v138, v138, v138
	v_max_f32_e32 v137, v137, v137
	v_max_f32_e32 v137, v137, v138
	s_cbranch_vccz .LBB0_514
	s_mov_b32 s2, 0x41000000
	v_cmp_lt_f32_e32 vcc, s2, v137
	s_mov_b64 s[30:31], 0
	s_mov_b64 s[28:29], 0
	s_cbranch_vccz .LBB0_500
	v_cndmask_b32_e32 v138, 0, v137, vcc
	s_mov_b64 s[28:29], -1
